# three GEMM K-loop heads aligned to 64 B (p2align 6) on top of packed SwiGLU epilogue
# baseline (speedup 1.0000x reference)
; template <class Epi, class Sched, bool ALIGN_EPI = false, bool SP2 = false>
; __device__ __forceinline__ void gemm_phase(PG8_LAS unsigned char* lds, const Gemm g, const Sched& S, const Epi& E) {
;     ...
;         const char* nA = has_next ? (const char*)g.A + (size_t)nxt.pm * tstep : cA; const char* nB = has_next ? (const char*)g.Bt + (size_t)nxt.pn * tstep : cB;
;         for (int t = 0; t < nt; t += 2) {
;             const bool last = (t == nt - 2);
;             const char* a1 = cA + (size_t)(t + 1) * kstep;
;             const char* a2 = last ? nA : cA + (size_t)(t + 2) * kstep; const char* b2 = last ? nB : cB + (size_t)(t + 2) * kstep;
;     ...
; #pragma unroll
;         for (int a = 0; a < 2; ++a)
; #pragma unroll
;             for (int b = 0; b < 2; ++b)
; #pragma unroll
;                 for (int m = 0; m < 4; ++m)
; #pragma unroll
;                     for (int n = 0; n < 2; ++n) acc[a][b][m][n] = (f32x4){0.f, 0.f, 0.f, 0.f};
.LBB0_606:
	s_ashr_i32 s23, s22, 31
	s_lshl_b64 s[24:25], s[22:23], 19
	s_add_u32 s24, s8, s24
	s_addc_u32 s25, s9, s25
	s_and_b64 s[26:27], s[2:3], exec
	s_cselect_b32 s23, s25, s29
	s_cselect_b32 s33, s24, s28
	s_ashr_i32 s21, s20, 31
	s_lshl_b64 s[26:27], s[20:21], 19
	s_add_u32 s26, s42, s26
	s_addc_u32 s27, s43, s27
	s_and_b64 s[34:35], s[2:3], exec
	s_cselect_b32 s21, s27, s31
	s_cselect_b32 s56, s26, s30
	s_add_u32 s28, s28, 0x40080
	s_addc_u32 s29, s29, 0
	s_add_u32 s57, s30, 0x100
	s_addc_u32 s58, s31, 0
	s_mov_b32 s59, -2
	v_mov_b64_e32 v[4:5], 0
	v_mov_b64_e32 v[6:7], 0
	v_mov_b64_e32 v[8:9], 0
	v_mov_b64_e32 v[10:11], 0
	v_mov_b64_e32 v[12:13], 0
	v_mov_b64_e32 v[14:15], 0
	v_mov_b64_e32 v[16:17], 0
	v_mov_b64_e32 v[18:19], 0
	v_mov_b64_e32 v[20:21], 0
	v_mov_b64_e32 v[22:23], 0
	v_mov_b64_e32 v[24:25], 0
	v_mov_b64_e32 v[26:27], 0
	v_mov_b64_e32 v[28:29], 0
	v_mov_b64_e32 v[30:31], 0
	v_mov_b64_e32 v[32:33], 0
	v_mov_b64_e32 v[34:35], 0
	v_mov_b64_e32 v[36:37], 0
	v_mov_b64_e32 v[38:39], 0
	v_mov_b64_e32 v[40:41], 0
	v_mov_b64_e32 v[42:43], 0
	v_mov_b64_e32 v[44:45], 0
	v_mov_b64_e32 v[46:47], 0
	v_mov_b64_e32 v[48:49], 0
	v_mov_b64_e32 v[50:51], 0
	v_mov_b64_e32 v[52:53], 0
	v_mov_b64_e32 v[54:55], 0
	v_mov_b64_e32 v[56:57], 0
	v_mov_b64_e32 v[58:59], 0
	v_mov_b64_e32 v[60:61], 0
	v_mov_b64_e32 v[62:63], 0
	v_mov_b64_e32 v[64:65], 0
	v_mov_b64_e32 v[66:67], 0
	v_mov_b64_e32 v[68:69], 0
	v_mov_b64_e32 v[70:71], 0
	v_mov_b64_e32 v[72:73], 0
	v_mov_b64_e32 v[74:75], 0
	v_mov_b64_e32 v[76:77], 0
	v_mov_b64_e32 v[78:79], 0
	v_mov_b64_e32 v[80:81], 0
	v_mov_b64_e32 v[82:83], 0
	v_mov_b64_e32 v[84:85], 0
	v_mov_b64_e32 v[86:87], 0
	v_mov_b64_e32 v[88:89], 0
	v_mov_b64_e32 v[90:91], 0
	v_mov_b64_e32 v[92:93], 0
	v_mov_b64_e32 v[94:95], 0
	v_mov_b64_e32 v[96:97], 0
	v_mov_b64_e32 v[98:99], 0
	v_mov_b64_e32 v[100:101], 0
	v_mov_b64_e32 v[102:103], 0
	v_mov_b64_e32 v[104:105], 0
	v_mov_b64_e32 v[106:107], 0
	v_mov_b64_e32 v[108:109], 0
	v_mov_b64_e32 v[110:111], 0
	v_mov_b64_e32 v[112:113], 0
	v_mov_b64_e32 v[114:115], 0
	v_mov_b64_e32 v[116:117], 0
	v_mov_b64_e32 v[118:119], 0
	v_mov_b64_e32 v[120:121], 0
	v_mov_b64_e32 v[122:123], 0
	v_mov_b64_e32 v[124:125], 0
	v_mov_b64_e32 v[126:127], 0
	v_mov_b64_e32 v[128:129], 0
	v_mov_b64_e32 v[130:131], 0
	.p2align 6

; template <class Epi, class Sched, bool ALIGN_EPI = false, bool SP2 = false>
; __device__ __forceinline__ void gemm_phase(PG8_LAS unsigned char* lds, const Gemm g, const Sched& S, const Epi& E) {
;     ...
; #pragma unroll
;         for (int a = 0; a < 2; ++a)
; #pragma unroll
;             for (int b = 0; b < 2; ++b)
; #pragma unroll
;                 for (int m = 0; m < 4; ++m)
; #pragma unroll
;                     for (int n = 0; n < 2; ++n) acc[a][b][m][n] = (f32x4){0.f, 0.f, 0.f, 0.f};
;         cur = nxt; cA = nA; cB = nB; ++ui;
.LBB0_637:
	s_add_u32 s26, s26, 0x80
	s_addc_u32 s27, s27, 0
	s_add_u32 s33, s28, 0x100
	s_addc_u32 s54, s29, 0
	s_mov_b32 s28, 0
	s_waitcnt lgkmcnt(0)
	v_mov_b64_e32 v[4:5], 0
	v_mov_b64_e32 v[6:7], 0
	v_mov_b64_e32 v[8:9], 0
	v_mov_b64_e32 v[10:11], 0
	v_mov_b64_e32 v[12:13], 0
	v_mov_b64_e32 v[14:15], 0
	v_mov_b64_e32 v[16:17], 0
	v_mov_b64_e32 v[18:19], 0
	v_mov_b64_e32 v[20:21], 0
	v_mov_b64_e32 v[22:23], 0
	v_mov_b64_e32 v[24:25], 0
	v_mov_b64_e32 v[26:27], 0
	v_mov_b64_e32 v[28:29], 0
	v_mov_b64_e32 v[30:31], 0
	v_mov_b64_e32 v[32:33], 0
	v_mov_b64_e32 v[34:35], 0
	v_mov_b64_e32 v[36:37], 0
	v_mov_b64_e32 v[38:39], 0
	v_mov_b64_e32 v[40:41], 0
	v_mov_b64_e32 v[42:43], 0
	v_mov_b64_e32 v[44:45], 0
	v_mov_b64_e32 v[46:47], 0
	v_mov_b64_e32 v[48:49], 0
	v_mov_b64_e32 v[50:51], 0
	v_mov_b64_e32 v[52:53], 0
	v_mov_b64_e32 v[54:55], 0
	v_mov_b64_e32 v[56:57], 0
	v_mov_b64_e32 v[58:59], 0
	v_mov_b64_e32 v[60:61], 0
	v_mov_b64_e32 v[62:63], 0
	v_mov_b64_e32 v[64:65], 0
	v_mov_b64_e32 v[66:67], 0
	v_mov_b64_e32 v[68:69], 0
	v_mov_b64_e32 v[70:71], 0
	v_mov_b64_e32 v[72:73], 0
	v_mov_b64_e32 v[74:75], 0
	v_mov_b64_e32 v[76:77], 0
	v_mov_b64_e32 v[78:79], 0
	v_mov_b64_e32 v[80:81], 0
	v_mov_b64_e32 v[82:83], 0
	v_mov_b64_e32 v[84:85], 0
	v_mov_b64_e32 v[86:87], 0
	v_mov_b64_e32 v[88:89], 0
	v_mov_b64_e32 v[90:91], 0
	v_mov_b64_e32 v[92:93], 0
	v_mov_b64_e32 v[94:95], 0
	v_mov_b64_e32 v[96:97], 0
	v_mov_b64_e32 v[98:99], 0
	v_mov_b64_e32 v[100:101], 0
	v_mov_b64_e32 v[102:103], 0
	v_mov_b64_e32 v[104:105], 0
	v_mov_b64_e32 v[106:107], 0
	v_mov_b64_e32 v[108:109], 0
	v_mov_b64_e32 v[110:111], 0
	v_mov_b64_e32 v[112:113], 0
	v_mov_b64_e32 v[114:115], 0
	v_mov_b64_e32 v[116:117], 0
	v_mov_b64_e32 v[118:119], 0
	v_mov_b64_e32 v[120:121], 0
	v_mov_b64_e32 v[122:123], 0
	v_mov_b64_e32 v[124:125], 0
	v_mov_b64_e32 v[126:127], 0
	v_mov_b64_e32 v[128:129], 0
	v_mov_b64_e32 v[130:131], 0
	.p2align 6

; template <class Epi, class Sched, bool ALIGN_EPI = false, bool SP2 = false>
; __device__ __forceinline__ void gemm_phase(PG8_LAS unsigned char* lds, const Gemm g, const Sched& S, const Epi& E) {
;     ...
;         const char* nA = has_next ? (const char*)g.A + (size_t)nxt.pm * tstep : cA; const char* nB = has_next ? (const char*)g.Bt + (size_t)nxt.pn * tstep : cB;
;         for (int t = 0; t < nt; t += 2) {
;             const bool last = (t == nt - 2);
;             const char* a1 = cA + (size_t)(t + 1) * kstep;
;             const char* a2 = last ? nA : cA + (size_t)(t + 2) * kstep; const char* b2 = last ? nB : cB + (size_t)(t + 2) * kstep;
;     ...
; #pragma unroll
;         for (int a = 0; a < 2; ++a)
; #pragma unroll
;             for (int b = 0; b < 2; ++b)
; #pragma unroll
;                 for (int m = 0; m < 4; ++m)
; #pragma unroll
;                     for (int n = 0; n < 2; ++n) acc[a][b][m][n] = (f32x4){0.f, 0.f, 0.f, 0.f};
.LBB0_684:
	s_ashr_i32 s35, s34, 31
	s_lshl_b64 s[36:37], s[34:35], 19
	s_add_u32 s36, s24, s36
	s_addc_u32 s37, s25, s37
	s_and_b64 s[38:39], s[2:3], exec
	s_cselect_b32 s33, s37, s43
	s_cselect_b32 s35, s36, s42
	s_ashr_i32 s31, s30, 31
	s_lshl_b64 s[38:39], s[30:31], 19
	s_add_u32 s38, s20, s38
	s_addc_u32 s39, s21, s39
	s_and_b64 s[46:47], s[2:3], exec
	s_cselect_b32 s31, s39, s45
	s_cselect_b32 s65, s38, s44
	s_add_u32 s42, s42, 0x40080
	s_addc_u32 s43, s43, 0
	s_add_u32 s66, s44, 0x100
	s_addc_u32 s67, s45, 0
	s_mov_b32 s68, -2
	v_mov_b64_e32 v[4:5], 0
	v_mov_b64_e32 v[6:7], 0
	v_mov_b64_e32 v[8:9], 0
	v_mov_b64_e32 v[10:11], 0
	v_mov_b64_e32 v[12:13], 0
	v_mov_b64_e32 v[14:15], 0
	v_mov_b64_e32 v[16:17], 0
	v_mov_b64_e32 v[18:19], 0
	v_mov_b64_e32 v[20:21], 0
	v_mov_b64_e32 v[22:23], 0
	v_mov_b64_e32 v[24:25], 0
	v_mov_b64_e32 v[26:27], 0
	v_mov_b64_e32 v[28:29], 0
	v_mov_b64_e32 v[30:31], 0
	v_mov_b64_e32 v[32:33], 0
	v_mov_b64_e32 v[34:35], 0
	v_mov_b64_e32 v[36:37], 0
	v_mov_b64_e32 v[38:39], 0
	v_mov_b64_e32 v[40:41], 0
	v_mov_b64_e32 v[42:43], 0
	v_mov_b64_e32 v[44:45], 0
	v_mov_b64_e32 v[46:47], 0
	v_mov_b64_e32 v[48:49], 0
	v_mov_b64_e32 v[50:51], 0
	v_mov_b64_e32 v[52:53], 0
	v_mov_b64_e32 v[54:55], 0
	v_mov_b64_e32 v[56:57], 0
	v_mov_b64_e32 v[58:59], 0
	v_mov_b64_e32 v[60:61], 0
	v_mov_b64_e32 v[62:63], 0
	v_mov_b64_e32 v[64:65], 0
	v_mov_b64_e32 v[66:67], 0
	v_mov_b64_e32 v[68:69], 0
	v_mov_b64_e32 v[70:71], 0
	v_mov_b64_e32 v[72:73], 0
	v_mov_b64_e32 v[74:75], 0
	v_mov_b64_e32 v[76:77], 0
	v_mov_b64_e32 v[78:79], 0
	v_mov_b64_e32 v[80:81], 0
	v_mov_b64_e32 v[82:83], 0
	v_mov_b64_e32 v[84:85], 0
	v_mov_b64_e32 v[86:87], 0
	v_mov_b64_e32 v[88:89], 0
	v_mov_b64_e32 v[90:91], 0
	v_mov_b64_e32 v[92:93], 0
	v_mov_b64_e32 v[94:95], 0
	v_mov_b64_e32 v[96:97], 0
	v_mov_b64_e32 v[98:99], 0
	v_mov_b64_e32 v[100:101], 0
	v_mov_b64_e32 v[102:103], 0
	v_mov_b64_e32 v[104:105], 0
	v_mov_b64_e32 v[106:107], 0
	v_mov_b64_e32 v[108:109], 0
	v_mov_b64_e32 v[110:111], 0
	v_mov_b64_e32 v[112:113], 0
	v_mov_b64_e32 v[114:115], 0
	v_mov_b64_e32 v[116:117], 0
	v_mov_b64_e32 v[118:119], 0
	v_mov_b64_e32 v[120:121], 0
	v_mov_b64_e32 v[122:123], 0
	v_mov_b64_e32 v[124:125], 0
	v_mov_b64_e32 v[126:127], 0
	v_mov_b64_e32 v[128:129], 0
	v_mov_b64_e32 v[130:131], 0
	.p2align 6
